# prologue balance: workgroups 0..31 skip the layer-0 MLP1 and GATE weight conversions (they run the cpart chain), workgroups 32.. cover them
# baseline (speedup 1.0000x reference)
.LBB0_66:
	s_cmpk_lt_i32 s2, 0x400
	v_mov_b32_e32 v2, v136
	s_cselect_b64 s[60:61], -1, 0
	s_cmpk_gt_i32 s2, 0x3ff
	s_cbranch_scc1 .LBB0_78
	s_load_dwordx4 s[12:15], s[0:1], 0x90
	s_waitcnt lgkmcnt(0)
	s_cmp_lt_u32 s2, 32
	s_cbranch_scc1 .LBB0_78
	s_sub_i32 s64, s2, 32
	s_sub_i32 s65, s34, 32
	s_add_u32 s8, s52, 0x6800000
	s_addc_u32 s9, s53, 0
	v_ashrrev_i32_e32 v1, 3, v2
	v_lshlrev_b32_e32 v2, 3, v2
	v_and_b32_e32 v10, 56, v2
	s_cmp_lg_u64 s[12:13], 0
	s_cselect_b64 s[6:7], -1, 0
	s_movk_i32 s3, 0x104
	v_lshl_add_u32 v4, v1, 2, 16
	v_mul_u32_u24_e32 v5, 0x104, v10
	v_lshl_add_u32 v2, v10, 2, 16
	v_mul_lo_u32 v3, v1, s3
	v_cndmask_b32_e64 v6, 0, 1, s[6:7]
	v_add_u32_e32 v15, v4, v5
	v_mov_b32_e32 v13, 0
	s_lshl_b32 s3, s64, 6
	s_lshl_b32 s4, s65, 6
	v_cmp_ne_u32_e64 s[6:7], 1, v6
	s_movk_i32 s5, 0x800
	v_add_u32_e32 v11, v2, v3
	v_lshlrev_b32_e32 v12, 1, v10
	v_add_u32_e32 v20, 0x400, v15
	s_mov_b32 s24, s64
	s_branch .LBB0_69
.LBB0_68:
	s_or_b64 exec, exec, s[22:23]
	s_add_i32 s24, s24, s65
	s_add_i32 s3, s3, s4
	s_cmpk_lt_i32 s24, 0x400
	s_barrier
	s_cbranch_scc0 .LBB0_78
